# full barriers b1/b2: hierarchical release (8 leaders poll TOP, each releases its XCD via a local word read with L2 atomics), on stack17
# speedup vs baseline: 1.0087x; 1.0007x over previous
; __device__ __forceinline__ unsigned xb_ld(unsigned* p)              { return __hip_atomic_load(p, __ATOMIC_RELAXED, __HIP_MEMORY_SCOPE_AGENT); }
; __device__ __forceinline__ unsigned xb_add(unsigned* p, unsigned v) { return __hip_atomic_fetch_add(p, v, __ATOMIC_RELAXED, __HIP_MEMORY_SCOPE_AGENT); }
; #define XB_SPIN(cond, bar) do { unsigned _sp = 0; while (cond) { __builtin_amdgcn_s_sleep(1); \
;     if ((++_sp & 255u) == 0u) { if (xb_ld(&(bar)[XB_TMO])) break; if (_sp > XB_SPIN_CAP) { atomicAdd(&(bar)[XB_TMO], 1u); break; } } } } while (0)
; __device__ __forceinline__ void xcd_barrier(const XcdBarrier& b) {
;     asm volatile("s_waitcnt vmcnt(0)" ::: "memory");
;     __syncthreads();
;     if (threadIdx.x == 0) {
;         unsigned* bar = b.bar;
;         __builtin_amdgcn_s_waitcnt(0);
;         unsigned nloc = b.st[0], nx = b.st[1];
;         if (nloc == 0u) { xcd_barrier_complete(bar, b.x, nloc, nx); b.st[0] = nloc; b.st[1] = nx; }
;         const unsigned old = xb_add(&bar[XB_XSUB(b.x)], 1u);
;         const unsigned gen = old / nloc;
;         if (old + 1u == (gen + 1u) * nloc) {
;             __builtin_amdgcn_fence(__ATOMIC_RELEASE, "agent");
;             asm volatile("s_waitcnt vmcnt(0)" ::: "memory");
;             const unsigned og = xb_add(&bar[XB_TOP], 1u);
;             const unsigned tg = og / nx;
;             if (og + 1u == (tg + 1u) * nx) xb_add(&bar[XB_TOPGEN], 1u);
;             else XB_SPIN(xb_ld(&bar[XB_TOPGEN]) == tg, bar);
;             __builtin_amdgcn_fence(__ATOMIC_ACQUIRE, "agent");
;             asm volatile("s_waitcnt vmcnt(0)" ::: "memory");
;         } else {
;             XB_SPIN(xb_ld(&bar[XB_TOPGEN]) == gen, bar);
;             __builtin_amdgcn_fence(__ATOMIC_ACQUIRE, "agent");
;             asm volatile("s_waitcnt vmcnt(0)" ::: "memory");
.LBB0_333:
	v_readlane_b32 s4, v253, 35
	v_readlane_b32 s5, v253, 36
	v_cvt_f32_u32_e32 v1, v2
	v_sub_u32_e32 v4, 0, v2
	v_rcp_iflag_f32_e32 v1, v1
	s_nop 1
	global_atomic_add v3, v177, v238, s[4:5] sc0
	v_mul_f32_e32 v1, 0x4f7ffffe, v1
	v_cvt_u32_f32_e32 v1, v1
	v_mul_lo_u32 v4, v4, v1
	v_mul_hi_u32 v4, v1, v4
	v_add_u32_e32 v1, v1, v4
	s_waitcnt vmcnt(0)
	v_mul_hi_u32 v1, v3, v1
	v_mul_lo_u32 v4, v1, v2
	v_sub_u32_e32 v4, v3, v4
	v_add_u32_e32 v5, 1, v1
	v_cmp_ge_u32_e32 vcc, v4, v2
	v_add_u32_e32 v3, 1, v3
	s_nop 0
	v_cndmask_b32_e32 v1, v1, v5, vcc
	v_sub_u32_e32 v5, v4, v2
	v_cndmask_b32_e32 v4, v4, v5, vcc
	v_add_u32_e32 v5, 1, v1
	v_cmp_ge_u32_e32 vcc, v4, v2
	s_nop 1
	v_cndmask_b32_e32 v1, v1, v5, vcc
	v_mul_lo_u32 v4, v2, v1
	v_add_u32_e32 v2, v4, v2
	v_cmp_ne_u32_e32 vcc, v3, v2
	s_waitcnt lgkmcnt(0)
	v_add_u32_e32 v4, 1, v1
	v_mul_lo_u32 v4, v4, v0
	v_readlane_b32 s98, v253, 39
	v_readlane_b32 s99, v253, 40
	s_nop 4
	s_cbranch_vccnz .Lxb_b1_nl
	buffer_wbl2 sc1
	s_waitcnt vmcnt(0)
	global_atomic_add v177, v238, s[98:99]
	buffer_inv sc1
	s_mov_b32 s100, 0

; __device__ __forceinline__ unsigned xb_ld(unsigned* p)              { return __hip_atomic_load(p, __ATOMIC_RELAXED, __HIP_MEMORY_SCOPE_AGENT); }
; __device__ __forceinline__ unsigned xb_add(unsigned* p, unsigned v) { return __hip_atomic_fetch_add(p, v, __ATOMIC_RELAXED, __HIP_MEMORY_SCOPE_AGENT); }
; #define XB_SPIN(cond, bar) do { unsigned _sp = 0; while (cond) { __builtin_amdgcn_s_sleep(1); \
;     if ((++_sp & 255u) == 0u) { if (xb_ld(&(bar)[XB_TMO])) break; if (_sp > XB_SPIN_CAP) { atomicAdd(&(bar)[XB_TMO], 1u); break; } } } } while (0)
; __device__ __forceinline__ void xcd_barrier(const XcdBarrier& b) {
;     ...
;             const unsigned tg = og / nx;
;             if (og + 1u == (tg + 1u) * nx) xb_add(&bar[XB_TOPGEN], 1u);
;             else XB_SPIN(xb_ld(&bar[XB_TOPGEN]) == tg, bar);
;             __builtin_amdgcn_fence(__ATOMIC_ACQUIRE, "agent");
;             asm volatile("s_waitcnt vmcnt(0)" ::: "memory");
;         } else {
;             XB_SPIN(xb_ld(&bar[XB_TOPGEN]) == gen, bar);
;             __builtin_amdgcn_fence(__ATOMIC_ACQUIRE, "agent");
;             asm volatile("s_waitcnt vmcnt(0)" ::: "memory");
.Lxb_b1_rel:
	v_add_u32_e32 v5, 1, v1
	global_atomic_umax v177, v5, s[4:5] offset:128
	s_branch .Lxb_b1_done
.Lxb_b1_nl:
	buffer_inv sc1
	v_add_u32_e32 v6, 1, v1
	s_mov_b32 s100, 0
.Lxb_b1_nspin:
	global_atomic_add v5, v177, v177, s[4:5] offset:128 sc0
	s_waitcnt vmcnt(0)
	v_cmp_ge_u32_e32 vcc, v5, v6
	s_cbranch_vccnz .Lxb_b1_done
	s_sleep 1
	s_add_i32 s100, s100, 1
	s_cmp_lt_u32 s100, 0x40000
	s_cbranch_scc1 .Lxb_b1_nspin

; __device__ __forceinline__ unsigned xb_ld(unsigned* p)              { return __hip_atomic_load(p, __ATOMIC_RELAXED, __HIP_MEMORY_SCOPE_AGENT); }
; __device__ __forceinline__ unsigned xb_add(unsigned* p, unsigned v) { return __hip_atomic_fetch_add(p, v, __ATOMIC_RELAXED, __HIP_MEMORY_SCOPE_AGENT); }
; #define XB_SPIN(cond, bar) do { unsigned _sp = 0; while (cond) { __builtin_amdgcn_s_sleep(1); \
;     if ((++_sp & 255u) == 0u) { if (xb_ld(&(bar)[XB_TMO])) break; if (_sp > XB_SPIN_CAP) { atomicAdd(&(bar)[XB_TMO], 1u); break; } } } } while (0)
; __device__ __forceinline__ void xcd_barrier(const XcdBarrier& b) {
;     ...
;         const unsigned old = xb_add(&bar[XB_XSUB(b.x)], 1u);
;         const unsigned gen = old / nloc;
;         if (old + 1u == (gen + 1u) * nloc) {
;             __builtin_amdgcn_fence(__ATOMIC_RELEASE, "agent");
;             asm volatile("s_waitcnt vmcnt(0)" ::: "memory");
;             const unsigned og = xb_add(&bar[XB_TOP], 1u);
;             const unsigned tg = og / nx;
;             if (og + 1u == (tg + 1u) * nx) xb_add(&bar[XB_TOPGEN], 1u);
;             else XB_SPIN(xb_ld(&bar[XB_TOPGEN]) == tg, bar);
;             __builtin_amdgcn_fence(__ATOMIC_ACQUIRE, "agent");
;             asm volatile("s_waitcnt vmcnt(0)" ::: "memory");
.Lxb_b2_full:
	s_cbranch_vccnz .Lxb_b2_nl
	buffer_wbl2 sc1
	s_waitcnt vmcnt(0)
	global_atomic_add v177, v238, s[98:99]
	buffer_inv sc1
	s_mov_b32 s100, 0
